# norm phase: SQ load issued first, split-K row loads (36) issued before the rstd pass consumes it, gains only loaded by the 512 waves that own a split-K row
# speedup vs baseline: 1.0163x; 1.0050x over previous
.LBB0_451:
	s_andn2_b64 vcc, exec, s[0:1]
	s_cbranch_vccnz .LBB0_457
	s_cmp_gt_i32 s20, 0x81ff
	s_cbranch_scc1 .LBB0_457
	s_waitcnt lgkmcnt(0)
	v_readlane_b32 s0, v255, 12
	v_readlane_b32 s1, v255, 13
	v_readlane_b32 s34, v251, 49
	v_readlane_b32 s35, v251, 50
	v_lshlrev_b32_e32 v130, 4, v189
	v_lshlrev_b32_e32 v131, 3, v189
	s_nop 1
	s_lshl_b32 s2, s20, 10
	v_add_u32_e32 v133, s2, v130
	v_add_u32_e32 v133, 0x4100000, v133
	global_load_dwordx4 v[138:141], v133, s[68:69]
	s_lshl_b32 s2, s20, 6
	v_lshrrev_b32_e32 v135, 2, v189
	v_lshl_add_u32 v135, v135, 2, s2
	v_add_u32_e32 v135, 0x4308000, v135
	s_cmp_gt_u32 s20, 511
	s_cbranch_scc1 .Lnrm_nosp
	global_load_dwordx4 v[48:51], v130, s[0:1]
	global_load_dwordx4 v[52:55], v130, s[0:1] offset:1024
	global_load_dwordx4 v[56:59], v130, s[0:1] offset:2048
	global_load_dwordx4 v[60:63], v130, s[0:1] offset:3072
	s_add_u32 s20, s20, 0x8000
	s_lshl_b32 s2, s20, 12
	v_add_u32_e32 v132, s2, v130
	global_load_dwordx4 v[0:3], v132, s[72:73] nt
	global_load_dwordx4 v[4:7], v132, s[72:73] offset:1024 nt
	global_load_dwordx4 v[8:11], v132, s[72:73] offset:2048 nt
	global_load_dwordx4 v[12:15], v132, s[72:73] offset:3072 nt
	s_sub_u32 s3, s20, 0x8000
	s_lshl_b32 s3, s3, 12
	v_add_u32_e32 v151, s3, v130
	s_mov_b32 s3, 0x200000
	global_load_dwordx4 v[64:67], v151, s[34:35]
	global_load_dwordx4 v[68:71], v151, s[34:35] offset:1024
	global_load_dwordx4 v[72:75], v151, s[34:35] offset:2048
	global_load_dwordx4 v[76:79], v151, s[34:35] offset:3072
	v_add_u32_e32 v151, s3, v151
	global_load_dwordx4 v[80:83], v151, s[34:35]
	global_load_dwordx4 v[84:87], v151, s[34:35] offset:1024
	global_load_dwordx4 v[88:91], v151, s[34:35] offset:2048
	global_load_dwordx4 v[92:95], v151, s[34:35] offset:3072
	v_add_u32_e32 v151, s3, v151
	global_load_dwordx4 v[96:99], v151, s[34:35]
	global_load_dwordx4 v[100:103], v151, s[34:35] offset:1024
	global_load_dwordx4 v[104:107], v151, s[34:35] offset:2048
	global_load_dwordx4 v[108:111], v151, s[34:35] offset:3072
	v_add_u32_e32 v151, s3, v151
	global_load_dwordx4 v[114:117], v151, s[34:35]
	global_load_dwordx4 v[118:121], v151, s[34:35] offset:1024
	global_load_dwordx4 v[122:125], v151, s[34:35] offset:2048
	global_load_dwordx4 v[126:129], v151, s[34:35] offset:3072
	v_add_u32_e32 v151, s3, v151
	global_load_dwordx4 v[16:19], v151, s[34:35]
	global_load_dwordx4 v[20:23], v151, s[34:35] offset:1024
	global_load_dwordx4 v[24:27], v151, s[34:35] offset:2048
	global_load_dwordx4 v[28:31], v151, s[34:35] offset:3072
	v_add_u32_e32 v151, s3, v151
	global_load_dwordx4 v[32:35], v151, s[34:35]
	global_load_dwordx4 v[36:39], v151, s[34:35] offset:1024
	global_load_dwordx4 v[40:43], v151, s[34:35] offset:2048
	global_load_dwordx4 v[44:47], v151, s[34:35] offset:3072
	v_add_u32_e32 v151, s3, v151
	global_load_dwordx4 v[192:195], v151, s[34:35]
	global_load_dwordx4 v[196:199], v151, s[34:35] offset:1024
	global_load_dwordx4 v[200:203], v151, s[34:35] offset:2048
	global_load_dwordx4 v[204:207], v151, s[34:35] offset:3072
	v_add_u32_e32 v151, s3, v151
	global_load_dwordx4 v[208:211], v151, s[34:35]
	global_load_dwordx4 v[212:215], v151, s[34:35] offset:1024
	global_load_dwordx4 v[216:219], v151, s[34:35] offset:2048
	global_load_dwordx4 v[220:223], v151, s[34:35] offset:3072
	s_mov_b32 s2, 0x11111111
	s_mov_b32 s3, 0x11111111
	s_waitcnt vmcnt(40)
	v_add_f32_e32 v138, v138, v139
	v_add_f32_e32 v140, v140, v141
	v_add_f32_e32 v134, v138, v140
	s_nop 1
	v_add_f32_dpp v134, v134, v134 quad_perm:[1,0,3,2] row_mask:0xf bank_mask:0xf
	s_nop 1
	v_add_f32_dpp v134, v134, v134 quad_perm:[2,3,0,1] row_mask:0xf bank_mask:0xf
	s_nop 0
	v_fmamk_f32 v134, v134, 0x3a800000, v172
	v_rsq_f32_e32 v134, v134
	s_mov_b64 exec, s[2:3]
	global_store_dword v135, v134, s[68:69]
	s_mov_b64 exec, -1
	s_waitcnt vmcnt(29)
	v_pk_add_f32 v[0:1], v[0:1], v[64:65]
	v_pk_add_f32 v[2:3], v[2:3], v[66:67]
	v_pk_add_f32 v[4:5], v[4:5], v[68:69]
	v_pk_add_f32 v[6:7], v[6:7], v[70:71]
	v_pk_add_f32 v[8:9], v[8:9], v[72:73]
	v_pk_add_f32 v[10:11], v[10:11], v[74:75]
	v_pk_add_f32 v[12:13], v[12:13], v[76:77]
	v_pk_add_f32 v[14:15], v[14:15], v[78:79]
	s_waitcnt vmcnt(25)
	v_pk_add_f32 v[0:1], v[0:1], v[80:81]
	v_pk_add_f32 v[2:3], v[2:3], v[82:83]
	v_pk_add_f32 v[4:5], v[4:5], v[84:85]
	v_pk_add_f32 v[6:7], v[6:7], v[86:87]
	v_pk_add_f32 v[8:9], v[8:9], v[88:89]
	v_pk_add_f32 v[10:11], v[10:11], v[90:91]
	v_pk_add_f32 v[12:13], v[12:13], v[92:93]
	v_pk_add_f32 v[14:15], v[14:15], v[94:95]
	s_waitcnt vmcnt(21)
	v_pk_add_f32 v[0:1], v[0:1], v[96:97]
	v_pk_add_f32 v[2:3], v[2:3], v[98:99]
	v_pk_add_f32 v[4:5], v[4:5], v[100:101]
	v_pk_add_f32 v[6:7], v[6:7], v[102:103]
	v_pk_add_f32 v[8:9], v[8:9], v[104:105]
	v_pk_add_f32 v[10:11], v[10:11], v[106:107]
	v_pk_add_f32 v[12:13], v[12:13], v[108:109]
	v_pk_add_f32 v[14:15], v[14:15], v[110:111]
	s_waitcnt vmcnt(17)
	v_pk_add_f32 v[0:1], v[0:1], v[114:115]
	v_pk_add_f32 v[2:3], v[2:3], v[116:117]
	v_pk_add_f32 v[4:5], v[4:5], v[118:119]
	v_pk_add_f32 v[6:7], v[6:7], v[120:121]
	v_pk_add_f32 v[8:9], v[8:9], v[122:123]
	v_pk_add_f32 v[10:11], v[10:11], v[124:125]
	v_pk_add_f32 v[12:13], v[12:13], v[126:127]
	v_pk_add_f32 v[14:15], v[14:15], v[128:129]
	s_waitcnt vmcnt(13)
	v_pk_add_f32 v[0:1], v[0:1], v[16:17]
	v_pk_add_f32 v[2:3], v[2:3], v[18:19]
	v_pk_add_f32 v[4:5], v[4:5], v[20:21]
	v_pk_add_f32 v[6:7], v[6:7], v[22:23]
	v_pk_add_f32 v[8:9], v[8:9], v[24:25]
	v_pk_add_f32 v[10:11], v[10:11], v[26:27]
	v_pk_add_f32 v[12:13], v[12:13], v[28:29]
	v_pk_add_f32 v[14:15], v[14:15], v[30:31]
	s_waitcnt vmcnt(9)
	v_pk_add_f32 v[0:1], v[0:1], v[32:33]
	v_pk_add_f32 v[2:3], v[2:3], v[34:35]
	v_pk_add_f32 v[4:5], v[4:5], v[36:37]
	v_pk_add_f32 v[6:7], v[6:7], v[38:39]
	v_pk_add_f32 v[8:9], v[8:9], v[40:41]
	v_pk_add_f32 v[10:11], v[10:11], v[42:43]
	v_pk_add_f32 v[12:13], v[12:13], v[44:45]
	v_pk_add_f32 v[14:15], v[14:15], v[46:47]
	s_waitcnt vmcnt(5)
	v_pk_add_f32 v[0:1], v[0:1], v[192:193]
	v_pk_add_f32 v[2:3], v[2:3], v[194:195]
	v_pk_add_f32 v[4:5], v[4:5], v[196:197]
	v_pk_add_f32 v[6:7], v[6:7], v[198:199]
	v_pk_add_f32 v[8:9], v[8:9], v[200:201]
	v_pk_add_f32 v[10:11], v[10:11], v[202:203]
	v_pk_add_f32 v[12:13], v[12:13], v[204:205]
	v_pk_add_f32 v[14:15], v[14:15], v[206:207]
	s_waitcnt vmcnt(1)
	v_pk_add_f32 v[0:1], v[0:1], v[208:209]
	v_pk_add_f32 v[2:3], v[2:3], v[210:211]
	v_pk_add_f32 v[4:5], v[4:5], v[212:213]
	v_pk_add_f32 v[6:7], v[6:7], v[214:215]
	v_pk_add_f32 v[8:9], v[8:9], v[216:217]
	v_pk_add_f32 v[10:11], v[10:11], v[218:219]
	v_pk_add_f32 v[12:13], v[12:13], v[220:221]
	v_pk_add_f32 v[14:15], v[14:15], v[222:223]
	global_store_dwordx4 v132, v[0:3], s[72:73]
	global_store_dwordx4 v132, v[4:7], s[72:73] offset:1024
	global_store_dwordx4 v132, v[8:11], s[72:73] offset:2048
	global_store_dwordx4 v132, v[12:15], s[72:73] offset:3072
	v_mul_f32_e32 v146, v0, v0
	v_mul_f32_e32 v147, v4, v4
	v_mul_f32_e32 v148, v8, v8
	v_mul_f32_e32 v149, v12, v12
	v_fmac_f32_e32 v146, v1, v1
	v_fmac_f32_e32 v147, v5, v5
	v_fmac_f32_e32 v148, v9, v9
	v_fmac_f32_e32 v149, v13, v13
	v_mul_f32_e32 v138, v2, v2
	v_mul_f32_e32 v139, v6, v6
	v_mul_f32_e32 v140, v10, v10
	v_mul_f32_e32 v141, v14, v14
	v_fmac_f32_e32 v138, v3, v3
	v_fmac_f32_e32 v139, v7, v7
	v_fmac_f32_e32 v140, v11, v11
	v_fmac_f32_e32 v141, v15, v15
	v_add_f32_e32 v146, v146, v138
	v_add_f32_e32 v147, v147, v139
	v_add_f32_e32 v148, v148, v140
	v_add_f32_e32 v149, v149, v141
	v_add_f32_e32 v134, v146, v147
	v_add_f32_e32 v134, v134, v148
	v_add_f32_e32 v134, v134, v149
	s_lshl_b32 s3, s20, 11
	s_nop 0
	v_add_f32_dpp v134, v134, v134 quad_perm:[1,0,3,2] row_mask:0xf bank_mask:0xf
	s_nop 1
	v_add_f32_dpp v134, v134, v134 quad_perm:[2,3,0,1] row_mask:0xf bank_mask:0xf
	s_nop 1
	v_add_f32_dpp v134, v134, v134 row_half_mirror row_mask:0xf bank_mask:0xf
	s_nop 1
	v_add_f32_dpp v134, v134, v134 row_mirror row_mask:0xf bank_mask:0xf
	s_nop 1
	v_add_f32_dpp v134, v134, v134 row_bcast:15 row_mask:0xa bank_mask:0xf
	s_nop 1
	v_add_f32_dpp v134, v134, v134 row_bcast:31 row_mask:0xc bank_mask:0xf
	s_nop 1
	v_readlane_b32 s10, v134, 63
	v_add_u32_e32 v133, s3, v131
	s_lshl_b32 s11, s20, 2
	s_add_u32 s11, s11, 0x4308000
	v_mov_b32_e32 v136, s10
	v_fmamk_f32 v136, v136, 0x3a800000, v172
	v_rsq_f32_e32 v136, v136
	v_mov_b32_e32 v137, s11
	s_nop 0
	global_store_dword v137, v136, s[68:69]
	v_pk_mul_f32 v[0:1], v[0:1], v[48:49]
	v_pk_mul_f32 v[2:3], v[2:3], v[50:51]
	v_pk_mul_f32 v[4:5], v[4:5], v[52:53]
	v_pk_mul_f32 v[6:7], v[6:7], v[54:55]
	v_pk_mul_f32 v[8:9], v[8:9], v[56:57]
	v_pk_mul_f32 v[10:11], v[10:11], v[58:59]
	v_pk_mul_f32 v[12:13], v[12:13], v[60:61]
	v_pk_mul_f32 v[14:15], v[14:15], v[62:63]
	v_cvt_pk_bf16_f32 v138, v0, v1
	v_cvt_pk_bf16_f32 v139, v2, v3
	v_cvt_pk_bf16_f32 v140, v4, v5
	v_cvt_pk_bf16_f32 v141, v6, v7
	v_cvt_pk_bf16_f32 v142, v8, v9
	v_cvt_pk_bf16_f32 v143, v10, v11
	v_cvt_pk_bf16_f32 v144, v12, v13
	v_cvt_pk_bf16_f32 v145, v14, v15
	global_store_dwordx2 v133, v[138:139], s[68:69]
	global_store_dwordx2 v133, v[140:141], s[68:69] offset:512
	global_store_dwordx2 v133, v[142:143], s[68:69] offset:1024
	global_store_dwordx2 v133, v[144:145], s[68:69] offset:1536
	s_branch .Lnrm_done
.Lnrm_nosp:
	s_mov_b32 s2, 0x11111111
	s_mov_b32 s3, 0x11111111
	s_waitcnt vmcnt(0)
	v_add_f32_e32 v138, v138, v139
	v_add_f32_e32 v140, v140, v141
	v_add_f32_e32 v134, v138, v140
	s_nop 1
	v_add_f32_dpp v134, v134, v134 quad_perm:[1,0,3,2] row_mask:0xf bank_mask:0xf
	s_nop 1
	v_add_f32_dpp v134, v134, v134 quad_perm:[2,3,0,1] row_mask:0xf bank_mask:0xf
	s_nop 0
	v_fmamk_f32 v134, v134, 0x3a800000, v172
	v_rsq_f32_e32 v134, v134
	s_mov_b64 exec, s[2:3]
	global_store_dword v135, v134, s[68:69]
	s_mov_b64 exec, -1
